# l0 token phase: loop-invariant norm gains loaded once before the row loop (were two load+drain round trips per row)
# speedup vs baseline: 1.0063x; 1.0063x over previous
.LBB0_641:
	s_cmp_gt_i32 s58, 3
	s_cselect_b64 s[2:3], -1, 0
	s_cmp_lt_i32 s59, 4
	s_cselect_b64 s[4:5], -1, 0
	s_or_b64 s[2:3], s[2:3], s[4:5]
	s_and_b64 vcc, exec, s[2:3]
	s_cbranch_vccnz .LBB0_711
	s_waitcnt vmcnt(0)
	v_mov_b32_e32 v7, 0
	ds_read_b64 v[2:3], v7 offset:416
	s_lshl_b32 s2, s30, 3
	s_add_i32 s6, s68, s2
	s_mov_b32 s5, 0
	s_cmpk_gt_i32 s6, 0x1bff
	s_waitcnt lgkmcnt(0)
	v_readfirstlane_b32 s10, v2
	v_readfirstlane_b32 s11, v3
	s_cbranch_scc1 .LBB0_654
	v_lshlrev_b32_e32 v6, 2, v198
	s_ashr_i32 s7, s6, 31
	v_lshl_add_u64 v[4:5], s[10:11], 0, v[6:7]
	s_mov_b64 s[12:13], 0x7c28000
	s_lshl_b64 s[14:15], s[6:7], 8
	v_lshl_add_u64 v[8:9], v[4:5], 0, s[12:13]
	v_or_b32_e32 v4, s14, v6
	v_mov_b32_e32 v5, s15
	s_lshl_b64 s[14:15], s[6:7], 7
	v_lshl_add_u64 v[10:11], v[4:5], 0, s[12:13]
	v_lshl_add_u64 v[4:5], s[14:15], 0, v[6:7]
	s_mov_b64 s[14:15], 0x1a00000
	s_lshl_b64 s[16:17], s[6:7], 9
	v_lshlrev_b32_e32 v1, 3, v198
	v_lshl_add_u64 v[12:13], v[4:5], 0, s[14:15]
	v_or_b32_e32 v4, s16, v1
	v_mov_b32_e32 v5, s17
	s_mov_b64 s[16:17], 0x7928000
	s_lshl_b64 s[20:21], s[6:7], 13
	v_lshl_add_u64 v[14:15], v[4:5], 0, s[16:17]
	v_or_b32_e32 v4, s20, v1
	v_mov_b32_e32 v5, s21
	s_mov_b64 s[18:19], 0x4928400
	v_lshl_add_u64 v[16:17], v[4:5], 0, s[18:19]
	v_or_b32_e32 v4, s20, v6
	s_mov_b64 s[22:23], 0x4928600
	s_lshl_b32 s8, s56, 3
	v_lshl_add_u64 v[18:19], v[4:5], 0, s[22:23]
	v_lshl_or_b32 v4, v198, 4, s20
	s_mov_b64 s[20:21], 0x4928000
	v_lshlrev_b32_e32 v2, 1, v198
	s_ashr_i32 s9, s8, 31
	v_lshl_add_u64 v[20:21], v[4:5], 0, s[20:21]
	s_brev_b32 s20, 60
	v_cmp_gt_u32_e64 s[2:3], 32, v198
	s_lshl_b64 s[12:13], s[8:9], 8
	s_lshl_b64 s[14:15], s[8:9], 7
	s_lshl_b64 s[16:17], s[8:9], 9
	s_lshl_b64 s[18:19], s[8:9], 13
	v_lshlrev_b32_e32 v1, 2, v6
	s_mov_b32 s21, 0x3b800000
	s_mov_b32 s9, 0x800000
	v_lshlrev_b32_e32 v24, 2, v2
	v_mov_b32_e32 v6, 0x358637bd
	ds_read_b128 v[206:209], v7 offset:224
	s_waitcnt lgkmcnt(0)
	v_readfirstlane_b32 s98, v206
	v_readfirstlane_b32 s99, v207
	v_readfirstlane_b32 s100, v208
	v_readfirstlane_b32 s101, v209
	s_nop 4
	global_load_dwordx4 v[200:203], v1, s[98:99]
	global_load_dwordx2 v[204:205], v24, s[100:101]
	s_branch .LBB0_646

.LBB0_651:
	s_or_b64 exec, exec, s[24:25]
	ds_read_b128 v[26:29], v7 offset:224
	s_waitcnt vmcnt(1)
	v_pk_mul_f32 v[34:35], v[2:3], v[2:3]
	s_waitcnt vmcnt(0)
	v_pk_mul_f32 v[36:37], v[22:23], v[22:23]
	v_add_f32_e32 v34, v34, v35
	v_add_f32_e32 v35, v36, v37
	s_waitcnt lgkmcnt(0)
	v_readfirstlane_b32 s24, v26
	v_readfirstlane_b32 s25, v27
	v_pk_mul_f32 v[26:27], v[4:5], v[4:5]
	s_nop 0
	v_add_f32_e32 v26, v26, v34
	v_add_f32_dpp v34, v35, v35 quad_perm:[1,0,3,2] row_mask:0xf bank_mask:0xf bound_ctrl:1
	v_add_f32_e32 v26, v27, v26
	v_mov_b64_e32 v[30:31], v[200:201]
	v_mov_b64_e32 v[32:33], v[202:203]
	v_add_f32_dpp v27, v34, v34 quad_perm:[2,3,0,1] row_mask:0xf bank_mask:0xf bound_ctrl:1
	v_add_f32_dpp v26, v26, v26 quad_perm:[1,0,3,2] row_mask:0xf bank_mask:0xf bound_ctrl:1
	s_nop 0
	v_add_f32_dpp v27, v27, v27 row_half_mirror row_mask:0xf bank_mask:0xf bound_ctrl:1
	v_add_f32_dpp v26, v26, v26 quad_perm:[2,3,0,1] row_mask:0xf bank_mask:0xf bound_ctrl:1
	s_nop 0
	v_add_f32_dpp v27, v27, v27 row_mirror row_mask:0xf bank_mask:0xf bound_ctrl:1
	v_add_f32_dpp v26, v26, v26 row_half_mirror row_mask:0xf bank_mask:0xf bound_ctrl:1
	v_readlane_b32 s4, v27, 16
	v_readlane_b32 s7, v27, 48
	v_add_f32_dpp v34, v26, v26 row_mirror row_mask:0xf bank_mask:0xf bound_ctrl:1
	v_readlane_b32 s24, v27, 0
	v_readlane_b32 s25, v27, 32
	v_mov_b32_e32 v26, s4
	v_mov_b32_e32 v27, s7
	v_readlane_b32 s4, v34, 16
	v_readlane_b32 s7, v34, 48
	v_readlane_b32 s26, v34, 0
	v_readlane_b32 s27, v34, 32
	v_mov_b32_e32 v34, s4
	v_mov_b32_e32 v35, s7
	v_pk_add_f32 v[26:27], s[24:25], v[26:27]
	v_pk_add_f32 v[34:35], s[26:27], v[34:35]
	v_mov_b32_e32 v36, v26
	v_mov_b32_e32 v37, v34
	v_mov_b32_e32 v34, v27
	v_pk_add_f32 v[26:27], v[36:37], v[34:35]
	v_readfirstlane_b32 s24, v28
	v_pk_fma_f32 v[26:27], v[26:27], s[20:21], v[6:7] op_sel_hi:[1,1,0]
	v_readfirstlane_b32 s25, v29
	v_mul_f32_e32 v34, 0x4b800000, v27
	v_cmp_gt_f32_e32 vcc, s9, v27
	s_nop 1
	v_cndmask_b32_e32 v27, v27, v34, vcc
	v_rsq_f32_e32 v27, v27
	v_lshl_add_u64 v[34:35], s[10:11], 0, v[14:15]
	v_mul_f32_e32 v28, 0x45800000, v27
	v_cndmask_b32_e32 v28, v27, v28, vcc
	v_pk_mul_f32 v[2:3], v[2:3], v[28:29] op_sel_hi:[1,0]
	v_pk_mul_f32 v[4:5], v[4:5], v[28:29] op_sel_hi:[1,0]
	v_cmp_gt_f32_e32 vcc, s9, v26
	s_nop 0
	v_pk_mul_f32 v[2:3], v[30:31], v[2:3]
	v_pk_mul_f32 v[4:5], v[32:33], v[4:5]
	v_cvt_pk_bf16_f32 v2, v2, v3
	v_cvt_pk_bf16_f32 v3, v4, v5
	global_store_dwordx2 v[34:35], v[2:3], off
	s_nop 1
	v_mov_b64_e32 v[2:3], v[204:205]
	v_mul_f32_e32 v4, 0x4b800000, v26
	v_cndmask_b32_e32 v4, v26, v4, vcc
	v_rsq_f32_e32 v4, v4
	v_lshl_add_u64 v[26:27], s[10:11], 0, v[10:11]
	v_mul_f32_e32 v5, 0x45800000, v4
	v_cndmask_b32_e32 v4, v4, v5, vcc
	v_pk_mul_f32 v[4:5], v[22:23], v[4:5] op_sel_hi:[1,0]
	s_andn2_b64 vcc, exec, s[22:23]
	s_nop 0
	v_pk_mul_f32 v[4:5], v[2:3], v[4:5]
	s_nop 0
	v_cvt_pk_bf16_f32 v2, v4, v5
	global_store_dword v[26:27], v2, off
	s_cbranch_vccnz .LBB0_645
	ds_read_b64 v[2:3], v7 offset:408
	s_waitcnt lgkmcnt(0)
	v_readfirstlane_b32 s22, v2
	v_readfirstlane_b32 s23, v3
	s_nop 1
	v_lshl_add_u64 v[22:23], s[22:23], 0, v[14:15]
	v_add_co_u32_e32 v22, vcc, 0xf9ed8000, v22
	s_nop 1
	v_addc_co_u32_e32 v23, vcc, -1, v23, vcc
	global_store_dwordx2 v[22:23], v[4:5], off
	s_and_saveexec_b64 s[22:23], s[2:3]
	s_cbranch_execz .LBB0_644
	v_readfirstlane_b32 s24, v2
	v_readfirstlane_b32 s25, v3
	s_nop 1
	v_lshl_add_u64 v[2:3], s[24:25], 0, v[12:13]
	global_store_dword v[2:3], v25, off
	s_branch .LBB0_644
